# GU SwiGLU epilogue: 60 of 64 per-element dependent chains regenerated with private temporaries and emitted 8-wide interleaved (no s_nop padding)
# speedup vs baseline: 1.0100x; 1.0035x over previous
.Lg16_gu_k:
	s_add_i32 s8, s1, 2
	s_lshl_b32 s96, s8, 13
	s_add_i32 m0, vcc_lo, 16384
	v_lshl_add_u64 v[160:161], v[188:189], 0, s[96:97]
	global_load_lds_dwordx4 v[160:161], off
	global_load_lds_dwordx4 v[160:161], off offset:1024
	ds_read_b128 v[196:199], v246 offset:0
	ds_read_b128 v[200:203], v246 offset:1024
	ds_read_b128 v[204:207], v246 offset:2048
	ds_read_b128 v[242:245], v246 offset:3072
	s_add_i32 s8, s1, 2
	s_lshl_b32 s96, s8, 11
	v_lshl_add_u64 v[248:249], v[184:185], 0, s[96:97]
	v_lshl_add_u64 v[250:251], v[186:187], 0, s[96:97]
	s_waitcnt vmcnt(8) lgkmcnt(3)
	v_mfma_f32_16x16x32_bf16 v[112:115], v[128:131], v[196:199], v[112:115]
	v_mfma_f32_16x16x32_bf16 v[120:123], v[132:135], v[196:199], v[120:123]
	v_mfma_f32_16x16x32_bf16 v[80:83], v[136:139], v[196:199], v[80:83]
	v_mfma_f32_16x16x32_bf16 v[88:91], v[140:143], v[196:199], v[88:91]
	ds_read_b128 v[196:199], v246 offset:4096
	s_waitcnt lgkmcnt(3)
	v_mfma_f32_16x16x32_bf16 v[116:119], v[128:131], v[200:203], v[116:119]
	v_mfma_f32_16x16x32_bf16 v[124:127], v[132:135], v[200:203], v[124:127]
	v_mfma_f32_16x16x32_bf16 v[84:87], v[136:139], v[200:203], v[84:87]
	v_mfma_f32_16x16x32_bf16 v[92:95], v[140:143], v[200:203], v[92:95]
	ds_read_b128 v[200:203], v246 offset:5120
	s_waitcnt lgkmcnt(3)
	v_mfma_f32_16x16x32_bf16 v[96:99], v[128:131], v[204:207], v[96:99]
	v_mfma_f32_16x16x32_bf16 v[104:107], v[132:135], v[204:207], v[104:107]
	v_mfma_f32_16x16x32_bf16 v[64:67], v[136:139], v[204:207], v[64:67]
	v_mfma_f32_16x16x32_bf16 v[72:75], v[140:143], v[204:207], v[72:75]
	ds_read_b128 v[204:207], v246 offset:6144
	s_waitcnt lgkmcnt(3)
	v_mfma_f32_16x16x32_bf16 v[100:103], v[128:131], v[242:245], v[100:103]
	v_mfma_f32_16x16x32_bf16 v[108:111], v[132:135], v[242:245], v[108:111]
	v_mfma_f32_16x16x32_bf16 v[68:71], v[136:139], v[242:245], v[68:71]
	v_mfma_f32_16x16x32_bf16 v[76:79], v[140:143], v[242:245], v[76:79]
	ds_read_b128 v[242:245], v246 offset:7168
	s_waitcnt lgkmcnt(3)
	v_mfma_f32_16x16x32_bf16 v[48:51], v[128:131], v[196:199], v[48:51]
	v_mfma_f32_16x16x32_bf16 v[56:59], v[132:135], v[196:199], v[56:59]
	v_mfma_f32_16x16x32_bf16 v[16:19], v[136:139], v[196:199], v[16:19]
	v_mfma_f32_16x16x32_bf16 v[24:27], v[140:143], v[196:199], v[24:27]
	s_waitcnt lgkmcnt(2)
	v_mfma_f32_16x16x32_bf16 v[52:55], v[128:131], v[200:203], v[52:55]
	v_mfma_f32_16x16x32_bf16 v[60:63], v[132:135], v[200:203], v[60:63]
	v_mfma_f32_16x16x32_bf16 v[20:23], v[136:139], v[200:203], v[20:23]
	v_mfma_f32_16x16x32_bf16 v[28:31], v[140:143], v[200:203], v[28:31]
	s_waitcnt lgkmcnt(1)
	v_mfma_f32_16x16x32_bf16 v[32:35], v[128:131], v[204:207], v[32:35]
	v_mfma_f32_16x16x32_bf16 v[40:43], v[132:135], v[204:207], v[40:43]
	v_mfma_f32_16x16x32_bf16 v[0:3], v[136:139], v[204:207], v[0:3]
	v_mfma_f32_16x16x32_bf16 v[8:11], v[140:143], v[204:207], v[8:11]
	s_waitcnt lgkmcnt(0)
	v_mfma_f32_16x16x32_bf16 v[36:39], v[128:131], v[242:245], v[36:39]
	v_mfma_f32_16x16x32_bf16 v[44:47], v[132:135], v[242:245], v[44:47]
	v_mfma_f32_16x16x32_bf16 v[4:7], v[136:139], v[242:245], v[4:7]
	v_mfma_f32_16x16x32_bf16 v[12:15], v[140:143], v[242:245], v[12:15]
	global_load_dwordx4 v[128:131], v[248:249], off
	global_load_dwordx4 v[132:135], v[248:249], off offset:256
	global_load_dwordx4 v[136:139], v[250:251], off
	global_load_dwordx4 v[140:143], v[250:251], off offset:256
	s_waitcnt vmcnt(10)
	s_barrier
	s_add_i32 s8, s1, 3
	s_lshl_b32 s96, s8, 13
	s_mov_b32 m0, vcc_lo
	v_lshl_add_u64 v[160:161], v[188:189], 0, s[96:97]
	global_load_lds_dwordx4 v[160:161], off
	global_load_lds_dwordx4 v[160:161], off offset:1024
	ds_read_b128 v[196:199], v246 offset:8192
	ds_read_b128 v[200:203], v246 offset:9216
	ds_read_b128 v[204:207], v246 offset:10240
	ds_read_b128 v[242:245], v246 offset:11264
	s_add_i32 s8, s1, 3
	s_lshl_b32 s96, s8, 11
	v_lshl_add_u64 v[248:249], v[184:185], 0, s[96:97]
	v_lshl_add_u64 v[250:251], v[186:187], 0, s[96:97]
	s_waitcnt vmcnt(8) lgkmcnt(3)
	v_mfma_f32_16x16x32_bf16 v[112:115], v[144:147], v[196:199], v[112:115]
	v_mfma_f32_16x16x32_bf16 v[120:123], v[148:151], v[196:199], v[120:123]
	v_mfma_f32_16x16x32_bf16 v[80:83], v[152:155], v[196:199], v[80:83]
	v_mfma_f32_16x16x32_bf16 v[88:91], v[156:159], v[196:199], v[88:91]
	ds_read_b128 v[196:199], v246 offset:12288
	s_waitcnt lgkmcnt(3)
	v_mfma_f32_16x16x32_bf16 v[116:119], v[144:147], v[200:203], v[116:119]
	v_mfma_f32_16x16x32_bf16 v[124:127], v[148:151], v[200:203], v[124:127]
	v_mfma_f32_16x16x32_bf16 v[84:87], v[152:155], v[200:203], v[84:87]
	v_mfma_f32_16x16x32_bf16 v[92:95], v[156:159], v[200:203], v[92:95]
	ds_read_b128 v[200:203], v246 offset:13312
	s_waitcnt lgkmcnt(3)
	v_mfma_f32_16x16x32_bf16 v[96:99], v[144:147], v[204:207], v[96:99]
	v_mfma_f32_16x16x32_bf16 v[104:107], v[148:151], v[204:207], v[104:107]
	v_mfma_f32_16x16x32_bf16 v[64:67], v[152:155], v[204:207], v[64:67]
	v_mfma_f32_16x16x32_bf16 v[72:75], v[156:159], v[204:207], v[72:75]
	ds_read_b128 v[204:207], v246 offset:14336
	s_waitcnt lgkmcnt(3)
	v_mfma_f32_16x16x32_bf16 v[100:103], v[144:147], v[242:245], v[100:103]
	v_mfma_f32_16x16x32_bf16 v[108:111], v[148:151], v[242:245], v[108:111]
	v_mfma_f32_16x16x32_bf16 v[68:71], v[152:155], v[242:245], v[68:71]
	v_mfma_f32_16x16x32_bf16 v[76:79], v[156:159], v[242:245], v[76:79]
	ds_read_b128 v[242:245], v246 offset:15360
	s_waitcnt lgkmcnt(3)
	v_mfma_f32_16x16x32_bf16 v[48:51], v[144:147], v[196:199], v[48:51]
	v_mfma_f32_16x16x32_bf16 v[56:59], v[148:151], v[196:199], v[56:59]
	v_mfma_f32_16x16x32_bf16 v[16:19], v[152:155], v[196:199], v[16:19]
	v_mfma_f32_16x16x32_bf16 v[24:27], v[156:159], v[196:199], v[24:27]
	s_waitcnt lgkmcnt(2)
	v_mfma_f32_16x16x32_bf16 v[52:55], v[144:147], v[200:203], v[52:55]
	v_mfma_f32_16x16x32_bf16 v[60:63], v[148:151], v[200:203], v[60:63]
	v_mfma_f32_16x16x32_bf16 v[20:23], v[152:155], v[200:203], v[20:23]
	v_mfma_f32_16x16x32_bf16 v[28:31], v[156:159], v[200:203], v[28:31]
	s_waitcnt lgkmcnt(1)
	v_mfma_f32_16x16x32_bf16 v[32:35], v[144:147], v[204:207], v[32:35]
	v_mfma_f32_16x16x32_bf16 v[40:43], v[148:151], v[204:207], v[40:43]
	v_mfma_f32_16x16x32_bf16 v[0:3], v[152:155], v[204:207], v[0:3]
	v_mfma_f32_16x16x32_bf16 v[8:11], v[156:159], v[204:207], v[8:11]
	s_waitcnt lgkmcnt(0)
	v_mfma_f32_16x16x32_bf16 v[36:39], v[144:147], v[242:245], v[36:39]
	v_mfma_f32_16x16x32_bf16 v[44:47], v[148:151], v[242:245], v[44:47]
	v_mfma_f32_16x16x32_bf16 v[4:7], v[152:155], v[242:245], v[4:7]
	v_mfma_f32_16x16x32_bf16 v[12:15], v[156:159], v[242:245], v[12:15]
	global_load_dwordx4 v[144:147], v[248:249], off
	global_load_dwordx4 v[148:151], v[248:249], off offset:256
	global_load_dwordx4 v[152:155], v[250:251], off
	global_load_dwordx4 v[156:159], v[250:251], off offset:256
	s_waitcnt vmcnt(10)
	s_barrier
	s_add_i32 s8, s1, 4
	s_lshl_b32 s96, s8, 13
	s_add_i32 m0, vcc_lo, 8192
	v_lshl_add_u64 v[160:161], v[188:189], 0, s[96:97]
	global_load_lds_dwordx4 v[160:161], off
	global_load_lds_dwordx4 v[160:161], off offset:1024
	ds_read_b128 v[196:199], v246 offset:16384
	ds_read_b128 v[200:203], v246 offset:17408
	ds_read_b128 v[204:207], v246 offset:18432
	ds_read_b128 v[242:245], v246 offset:19456
	s_add_i32 s8, s1, 4
	s_lshl_b32 s96, s8, 11
	v_lshl_add_u64 v[248:249], v[184:185], 0, s[96:97]
	v_lshl_add_u64 v[250:251], v[186:187], 0, s[96:97]
	s_waitcnt vmcnt(8) lgkmcnt(3)
	v_mfma_f32_16x16x32_bf16 v[112:115], v[128:131], v[196:199], v[112:115]
	v_mfma_f32_16x16x32_bf16 v[120:123], v[132:135], v[196:199], v[120:123]
	v_mfma_f32_16x16x32_bf16 v[80:83], v[136:139], v[196:199], v[80:83]
	v_mfma_f32_16x16x32_bf16 v[88:91], v[140:143], v[196:199], v[88:91]
	ds_read_b128 v[196:199], v246 offset:20480
	s_waitcnt lgkmcnt(3)
	v_mfma_f32_16x16x32_bf16 v[116:119], v[128:131], v[200:203], v[116:119]
	v_mfma_f32_16x16x32_bf16 v[124:127], v[132:135], v[200:203], v[124:127]
	v_mfma_f32_16x16x32_bf16 v[84:87], v[136:139], v[200:203], v[84:87]
	v_mfma_f32_16x16x32_bf16 v[92:95], v[140:143], v[200:203], v[92:95]
	ds_read_b128 v[200:203], v246 offset:21504
	s_waitcnt lgkmcnt(3)
	v_mfma_f32_16x16x32_bf16 v[96:99], v[128:131], v[204:207], v[96:99]
	v_mfma_f32_16x16x32_bf16 v[104:107], v[132:135], v[204:207], v[104:107]
	v_mfma_f32_16x16x32_bf16 v[64:67], v[136:139], v[204:207], v[64:67]
	v_mfma_f32_16x16x32_bf16 v[72:75], v[140:143], v[204:207], v[72:75]
	ds_read_b128 v[204:207], v246 offset:22528
	s_waitcnt lgkmcnt(3)
	v_mfma_f32_16x16x32_bf16 v[100:103], v[128:131], v[242:245], v[100:103]
	v_mfma_f32_16x16x32_bf16 v[108:111], v[132:135], v[242:245], v[108:111]
	v_mfma_f32_16x16x32_bf16 v[68:71], v[136:139], v[242:245], v[68:71]
	v_mfma_f32_16x16x32_bf16 v[76:79], v[140:143], v[242:245], v[76:79]
	ds_read_b128 v[242:245], v246 offset:23552
	s_waitcnt lgkmcnt(3)
	v_mfma_f32_16x16x32_bf16 v[48:51], v[128:131], v[196:199], v[48:51]
	v_mfma_f32_16x16x32_bf16 v[56:59], v[132:135], v[196:199], v[56:59]
	v_mfma_f32_16x16x32_bf16 v[16:19], v[136:139], v[196:199], v[16:19]
	v_mfma_f32_16x16x32_bf16 v[24:27], v[140:143], v[196:199], v[24:27]
	s_waitcnt lgkmcnt(2)
	v_mfma_f32_16x16x32_bf16 v[52:55], v[128:131], v[200:203], v[52:55]
	v_mfma_f32_16x16x32_bf16 v[60:63], v[132:135], v[200:203], v[60:63]
	v_mfma_f32_16x16x32_bf16 v[20:23], v[136:139], v[200:203], v[20:23]
	v_mfma_f32_16x16x32_bf16 v[28:31], v[140:143], v[200:203], v[28:31]
	s_waitcnt lgkmcnt(1)
	v_mfma_f32_16x16x32_bf16 v[32:35], v[128:131], v[204:207], v[32:35]
	v_mfma_f32_16x16x32_bf16 v[40:43], v[132:135], v[204:207], v[40:43]
	v_mfma_f32_16x16x32_bf16 v[0:3], v[136:139], v[204:207], v[0:3]
	v_mfma_f32_16x16x32_bf16 v[8:11], v[140:143], v[204:207], v[8:11]
	s_waitcnt lgkmcnt(0)
	v_mfma_f32_16x16x32_bf16 v[36:39], v[128:131], v[242:245], v[36:39]
	v_mfma_f32_16x16x32_bf16 v[44:47], v[132:135], v[242:245], v[44:47]
	v_mfma_f32_16x16x32_bf16 v[4:7], v[136:139], v[242:245], v[4:7]
	v_mfma_f32_16x16x32_bf16 v[12:15], v[140:143], v[242:245], v[12:15]
	global_load_dwordx4 v[128:131], v[248:249], off
	global_load_dwordx4 v[132:135], v[248:249], off offset:256
	global_load_dwordx4 v[136:139], v[250:251], off
	global_load_dwordx4 v[140:143], v[250:251], off offset:256
	s_waitcnt vmcnt(10)
	s_barrier
	s_add_i32 s8, s1, 5
	s_lshl_b32 s96, s8, 13
	s_add_i32 m0, vcc_lo, 16384
	v_lshl_add_u64 v[160:161], v[188:189], 0, s[96:97]
	global_load_lds_dwordx4 v[160:161], off
	global_load_lds_dwordx4 v[160:161], off offset:1024
	ds_read_b128 v[196:199], v246 offset:0
	ds_read_b128 v[200:203], v246 offset:1024
	ds_read_b128 v[204:207], v246 offset:2048
	ds_read_b128 v[242:245], v246 offset:3072
	s_add_i32 s8, s1, 5
	s_lshl_b32 s96, s8, 11
	v_lshl_add_u64 v[248:249], v[184:185], 0, s[96:97]
	v_lshl_add_u64 v[250:251], v[186:187], 0, s[96:97]
	s_waitcnt vmcnt(8) lgkmcnt(3)
	v_mfma_f32_16x16x32_bf16 v[112:115], v[144:147], v[196:199], v[112:115]
	v_mfma_f32_16x16x32_bf16 v[120:123], v[148:151], v[196:199], v[120:123]
	v_mfma_f32_16x16x32_bf16 v[80:83], v[152:155], v[196:199], v[80:83]
	v_mfma_f32_16x16x32_bf16 v[88:91], v[156:159], v[196:199], v[88:91]
	ds_read_b128 v[196:199], v246 offset:4096
	s_waitcnt lgkmcnt(3)
	v_mfma_f32_16x16x32_bf16 v[116:119], v[144:147], v[200:203], v[116:119]
	v_mfma_f32_16x16x32_bf16 v[124:127], v[148:151], v[200:203], v[124:127]
	v_mfma_f32_16x16x32_bf16 v[84:87], v[152:155], v[200:203], v[84:87]
	v_mfma_f32_16x16x32_bf16 v[92:95], v[156:159], v[200:203], v[92:95]
	ds_read_b128 v[200:203], v246 offset:5120
	s_waitcnt lgkmcnt(3)
	v_mfma_f32_16x16x32_bf16 v[96:99], v[144:147], v[204:207], v[96:99]
	v_mfma_f32_16x16x32_bf16 v[104:107], v[148:151], v[204:207], v[104:107]
	v_mfma_f32_16x16x32_bf16 v[64:67], v[152:155], v[204:207], v[64:67]
	v_mfma_f32_16x16x32_bf16 v[72:75], v[156:159], v[204:207], v[72:75]
	ds_read_b128 v[204:207], v246 offset:6144
	s_waitcnt lgkmcnt(3)
	v_mfma_f32_16x16x32_bf16 v[100:103], v[144:147], v[242:245], v[100:103]
	v_mfma_f32_16x16x32_bf16 v[108:111], v[148:151], v[242:245], v[108:111]
	v_mfma_f32_16x16x32_bf16 v[68:71], v[152:155], v[242:245], v[68:71]
	v_mfma_f32_16x16x32_bf16 v[76:79], v[156:159], v[242:245], v[76:79]
	ds_read_b128 v[242:245], v246 offset:7168
	s_waitcnt lgkmcnt(3)
	v_mfma_f32_16x16x32_bf16 v[48:51], v[144:147], v[196:199], v[48:51]
	v_mfma_f32_16x16x32_bf16 v[56:59], v[148:151], v[196:199], v[56:59]
	v_mfma_f32_16x16x32_bf16 v[16:19], v[152:155], v[196:199], v[16:19]
	v_mfma_f32_16x16x32_bf16 v[24:27], v[156:159], v[196:199], v[24:27]
	s_waitcnt lgkmcnt(2)
	v_mfma_f32_16x16x32_bf16 v[52:55], v[144:147], v[200:203], v[52:55]
	v_mfma_f32_16x16x32_bf16 v[60:63], v[148:151], v[200:203], v[60:63]
	v_mfma_f32_16x16x32_bf16 v[20:23], v[152:155], v[200:203], v[20:23]
	v_mfma_f32_16x16x32_bf16 v[28:31], v[156:159], v[200:203], v[28:31]
	s_waitcnt lgkmcnt(1)
	v_mfma_f32_16x16x32_bf16 v[32:35], v[144:147], v[204:207], v[32:35]
	v_mfma_f32_16x16x32_bf16 v[40:43], v[148:151], v[204:207], v[40:43]
	v_mfma_f32_16x16x32_bf16 v[0:3], v[152:155], v[204:207], v[0:3]
	v_mfma_f32_16x16x32_bf16 v[8:11], v[156:159], v[204:207], v[8:11]
	s_waitcnt lgkmcnt(0)
	v_mfma_f32_16x16x32_bf16 v[36:39], v[144:147], v[242:245], v[36:39]
	v_mfma_f32_16x16x32_bf16 v[44:47], v[148:151], v[242:245], v[44:47]
	v_mfma_f32_16x16x32_bf16 v[4:7], v[152:155], v[242:245], v[4:7]
	v_mfma_f32_16x16x32_bf16 v[12:15], v[156:159], v[242:245], v[12:15]
	global_load_dwordx4 v[144:147], v[248:249], off
	global_load_dwordx4 v[148:151], v[248:249], off offset:256
	global_load_dwordx4 v[152:155], v[250:251], off
	global_load_dwordx4 v[156:159], v[250:251], off offset:256
	s_waitcnt vmcnt(10)
	s_barrier
	s_add_i32 s8, s1, 6
	s_lshl_b32 s96, s8, 13
	s_mov_b32 m0, vcc_lo
	v_lshl_add_u64 v[160:161], v[188:189], 0, s[96:97]
	global_load_lds_dwordx4 v[160:161], off
	global_load_lds_dwordx4 v[160:161], off offset:1024
	ds_read_b128 v[196:199], v246 offset:8192
	ds_read_b128 v[200:203], v246 offset:9216
	ds_read_b128 v[204:207], v246 offset:10240
	ds_read_b128 v[242:245], v246 offset:11264
	s_add_i32 s8, s1, 6
	s_lshl_b32 s96, s8, 11
	v_lshl_add_u64 v[248:249], v[184:185], 0, s[96:97]
	v_lshl_add_u64 v[250:251], v[186:187], 0, s[96:97]
	s_waitcnt vmcnt(8) lgkmcnt(3)
	v_mfma_f32_16x16x32_bf16 v[112:115], v[128:131], v[196:199], v[112:115]
	v_mfma_f32_16x16x32_bf16 v[120:123], v[132:135], v[196:199], v[120:123]
	v_mfma_f32_16x16x32_bf16 v[80:83], v[136:139], v[196:199], v[80:83]
	v_mfma_f32_16x16x32_bf16 v[88:91], v[140:143], v[196:199], v[88:91]
	ds_read_b128 v[196:199], v246 offset:12288
	s_waitcnt lgkmcnt(3)
	v_mfma_f32_16x16x32_bf16 v[116:119], v[128:131], v[200:203], v[116:119]
	v_mfma_f32_16x16x32_bf16 v[124:127], v[132:135], v[200:203], v[124:127]
	v_mfma_f32_16x16x32_bf16 v[84:87], v[136:139], v[200:203], v[84:87]
	v_mfma_f32_16x16x32_bf16 v[92:95], v[140:143], v[200:203], v[92:95]
	ds_read_b128 v[200:203], v246 offset:13312
	s_waitcnt lgkmcnt(3)
	v_mfma_f32_16x16x32_bf16 v[96:99], v[128:131], v[204:207], v[96:99]
	v_mfma_f32_16x16x32_bf16 v[104:107], v[132:135], v[204:207], v[104:107]
	v_mfma_f32_16x16x32_bf16 v[64:67], v[136:139], v[204:207], v[64:67]
	v_mfma_f32_16x16x32_bf16 v[72:75], v[140:143], v[204:207], v[72:75]
	ds_read_b128 v[204:207], v246 offset:14336
	s_waitcnt lgkmcnt(3)
	v_mfma_f32_16x16x32_bf16 v[100:103], v[128:131], v[242:245], v[100:103]
	v_mfma_f32_16x16x32_bf16 v[108:111], v[132:135], v[242:245], v[108:111]
	v_mfma_f32_16x16x32_bf16 v[68:71], v[136:139], v[242:245], v[68:71]
	v_mfma_f32_16x16x32_bf16 v[76:79], v[140:143], v[242:245], v[76:79]
	ds_read_b128 v[242:245], v246 offset:15360
	s_waitcnt lgkmcnt(3)
	v_mfma_f32_16x16x32_bf16 v[48:51], v[128:131], v[196:199], v[48:51]
	v_mfma_f32_16x16x32_bf16 v[56:59], v[132:135], v[196:199], v[56:59]
	v_mfma_f32_16x16x32_bf16 v[16:19], v[136:139], v[196:199], v[16:19]
	v_mfma_f32_16x16x32_bf16 v[24:27], v[140:143], v[196:199], v[24:27]
	s_waitcnt lgkmcnt(2)
	v_mfma_f32_16x16x32_bf16 v[52:55], v[128:131], v[200:203], v[52:55]
	v_mfma_f32_16x16x32_bf16 v[60:63], v[132:135], v[200:203], v[60:63]
	v_mfma_f32_16x16x32_bf16 v[20:23], v[136:139], v[200:203], v[20:23]
	v_mfma_f32_16x16x32_bf16 v[28:31], v[140:143], v[200:203], v[28:31]
	s_waitcnt lgkmcnt(1)
	v_mfma_f32_16x16x32_bf16 v[32:35], v[128:131], v[204:207], v[32:35]
	v_mfma_f32_16x16x32_bf16 v[40:43], v[132:135], v[204:207], v[40:43]
	v_mfma_f32_16x16x32_bf16 v[0:3], v[136:139], v[204:207], v[0:3]
	v_mfma_f32_16x16x32_bf16 v[8:11], v[140:143], v[204:207], v[8:11]
	s_waitcnt lgkmcnt(0)
	v_mfma_f32_16x16x32_bf16 v[36:39], v[128:131], v[242:245], v[36:39]
	v_mfma_f32_16x16x32_bf16 v[44:47], v[132:135], v[242:245], v[44:47]
	v_mfma_f32_16x16x32_bf16 v[4:7], v[136:139], v[242:245], v[4:7]
	v_mfma_f32_16x16x32_bf16 v[12:15], v[140:143], v[242:245], v[12:15]
	global_load_dwordx4 v[128:131], v[248:249], off
	global_load_dwordx4 v[132:135], v[248:249], off offset:256
	global_load_dwordx4 v[136:139], v[250:251], off
	global_load_dwordx4 v[140:143], v[250:251], off offset:256
	s_waitcnt vmcnt(10)
	s_barrier
	s_add_i32 s8, s1, 7
	s_lshl_b32 s96, s8, 13
	s_add_i32 m0, vcc_lo, 8192
	v_lshl_add_u64 v[160:161], v[188:189], 0, s[96:97]
	global_load_lds_dwordx4 v[160:161], off
	global_load_lds_dwordx4 v[160:161], off offset:1024
	ds_read_b128 v[196:199], v246 offset:16384
	ds_read_b128 v[200:203], v246 offset:17408
	ds_read_b128 v[204:207], v246 offset:18432
	ds_read_b128 v[242:245], v246 offset:19456
	s_add_i32 s8, s1, 7
	s_lshl_b32 s96, s8, 11
	v_lshl_add_u64 v[248:249], v[184:185], 0, s[96:97]
	v_lshl_add_u64 v[250:251], v[186:187], 0, s[96:97]
	s_waitcnt vmcnt(8) lgkmcnt(3)
	v_mfma_f32_16x16x32_bf16 v[112:115], v[144:147], v[196:199], v[112:115]
	v_mfma_f32_16x16x32_bf16 v[120:123], v[148:151], v[196:199], v[120:123]
	v_mfma_f32_16x16x32_bf16 v[80:83], v[152:155], v[196:199], v[80:83]
	v_mfma_f32_16x16x32_bf16 v[88:91], v[156:159], v[196:199], v[88:91]
	ds_read_b128 v[196:199], v246 offset:20480
	s_waitcnt lgkmcnt(3)
	v_mfma_f32_16x16x32_bf16 v[116:119], v[144:147], v[200:203], v[116:119]
	v_mfma_f32_16x16x32_bf16 v[124:127], v[148:151], v[200:203], v[124:127]
	v_mfma_f32_16x16x32_bf16 v[84:87], v[152:155], v[200:203], v[84:87]
	v_mfma_f32_16x16x32_bf16 v[92:95], v[156:159], v[200:203], v[92:95]
	ds_read_b128 v[200:203], v246 offset:21504
	s_waitcnt lgkmcnt(3)
	v_mfma_f32_16x16x32_bf16 v[96:99], v[144:147], v[204:207], v[96:99]
	v_mfma_f32_16x16x32_bf16 v[104:107], v[148:151], v[204:207], v[104:107]
	v_mfma_f32_16x16x32_bf16 v[64:67], v[152:155], v[204:207], v[64:67]
	v_mfma_f32_16x16x32_bf16 v[72:75], v[156:159], v[204:207], v[72:75]
	ds_read_b128 v[204:207], v246 offset:22528
	s_waitcnt lgkmcnt(3)
	v_mfma_f32_16x16x32_bf16 v[100:103], v[144:147], v[242:245], v[100:103]
	v_mfma_f32_16x16x32_bf16 v[108:111], v[148:151], v[242:245], v[108:111]
	v_mfma_f32_16x16x32_bf16 v[68:71], v[152:155], v[242:245], v[68:71]
	v_mfma_f32_16x16x32_bf16 v[76:79], v[156:159], v[242:245], v[76:79]
	ds_read_b128 v[242:245], v246 offset:23552
	s_waitcnt lgkmcnt(3)
	v_mfma_f32_16x16x32_bf16 v[48:51], v[144:147], v[196:199], v[48:51]
	v_mfma_f32_16x16x32_bf16 v[56:59], v[148:151], v[196:199], v[56:59]
	v_mfma_f32_16x16x32_bf16 v[16:19], v[152:155], v[196:199], v[16:19]
	v_mfma_f32_16x16x32_bf16 v[24:27], v[156:159], v[196:199], v[24:27]
	s_waitcnt lgkmcnt(2)
	v_mfma_f32_16x16x32_bf16 v[52:55], v[144:147], v[200:203], v[52:55]
	v_mfma_f32_16x16x32_bf16 v[60:63], v[148:151], v[200:203], v[60:63]
	v_mfma_f32_16x16x32_bf16 v[20:23], v[152:155], v[200:203], v[20:23]
	v_mfma_f32_16x16x32_bf16 v[28:31], v[156:159], v[200:203], v[28:31]
	s_waitcnt lgkmcnt(1)
	v_mfma_f32_16x16x32_bf16 v[32:35], v[144:147], v[204:207], v[32:35]
	v_mfma_f32_16x16x32_bf16 v[40:43], v[148:151], v[204:207], v[40:43]
	v_mfma_f32_16x16x32_bf16 v[0:3], v[152:155], v[204:207], v[0:3]
	v_mfma_f32_16x16x32_bf16 v[8:11], v[156:159], v[204:207], v[8:11]
	s_waitcnt lgkmcnt(0)
	v_mfma_f32_16x16x32_bf16 v[36:39], v[144:147], v[242:245], v[36:39]
	v_mfma_f32_16x16x32_bf16 v[44:47], v[148:151], v[242:245], v[44:47]
	v_mfma_f32_16x16x32_bf16 v[4:7], v[152:155], v[242:245], v[4:7]
	v_mfma_f32_16x16x32_bf16 v[12:15], v[156:159], v[242:245], v[12:15]
	global_load_dwordx4 v[144:147], v[248:249], off
	global_load_dwordx4 v[148:151], v[248:249], off offset:256
	global_load_dwordx4 v[152:155], v[250:251], off
	global_load_dwordx4 v[156:159], v[250:251], off offset:256
	s_waitcnt vmcnt(10)
	s_barrier
	s_add_i32 s1, s1, 6
	s_cmp_lt_u32 s1, 30
	s_cbranch_scc1 .Lg16_gu_k
	ds_read_b128 v[196:199], v246 offset:0
	ds_read_b128 v[200:203], v246 offset:1024
	ds_read_b128 v[204:207], v246 offset:2048
	ds_read_b128 v[242:245], v246 offset:3072
	s_waitcnt vmcnt(6) lgkmcnt(3)
	v_mfma_f32_16x16x32_bf16 v[112:115], v[128:131], v[196:199], v[112:115]
	v_mfma_f32_16x16x32_bf16 v[120:123], v[132:135], v[196:199], v[120:123]
	v_mfma_f32_16x16x32_bf16 v[80:83], v[136:139], v[196:199], v[80:83]
	v_mfma_f32_16x16x32_bf16 v[88:91], v[140:143], v[196:199], v[88:91]
	ds_read_b128 v[196:199], v246 offset:4096
	s_waitcnt lgkmcnt(3)
	v_mfma_f32_16x16x32_bf16 v[116:119], v[128:131], v[200:203], v[116:119]
	v_mfma_f32_16x16x32_bf16 v[124:127], v[132:135], v[200:203], v[124:127]
	v_mfma_f32_16x16x32_bf16 v[84:87], v[136:139], v[200:203], v[84:87]
	v_mfma_f32_16x16x32_bf16 v[92:95], v[140:143], v[200:203], v[92:95]
	ds_read_b128 v[200:203], v246 offset:5120
	s_waitcnt lgkmcnt(3)
	v_mfma_f32_16x16x32_bf16 v[96:99], v[128:131], v[204:207], v[96:99]
	v_mfma_f32_16x16x32_bf16 v[104:107], v[132:135], v[204:207], v[104:107]
	v_mfma_f32_16x16x32_bf16 v[64:67], v[136:139], v[204:207], v[64:67]
	v_mfma_f32_16x16x32_bf16 v[72:75], v[140:143], v[204:207], v[72:75]
	ds_read_b128 v[204:207], v246 offset:6144
	s_waitcnt lgkmcnt(3)
	v_mfma_f32_16x16x32_bf16 v[100:103], v[128:131], v[242:245], v[100:103]
	v_mfma_f32_16x16x32_bf16 v[108:111], v[132:135], v[242:245], v[108:111]
	v_mfma_f32_16x16x32_bf16 v[68:71], v[136:139], v[242:245], v[68:71]
	v_mfma_f32_16x16x32_bf16 v[76:79], v[140:143], v[242:245], v[76:79]
	ds_read_b128 v[242:245], v246 offset:7168
	s_waitcnt lgkmcnt(3)
	v_mfma_f32_16x16x32_bf16 v[48:51], v[128:131], v[196:199], v[48:51]
	v_mfma_f32_16x16x32_bf16 v[56:59], v[132:135], v[196:199], v[56:59]
	v_mfma_f32_16x16x32_bf16 v[16:19], v[136:139], v[196:199], v[16:19]
	v_mfma_f32_16x16x32_bf16 v[24:27], v[140:143], v[196:199], v[24:27]
	s_waitcnt lgkmcnt(2)
	v_mfma_f32_16x16x32_bf16 v[52:55], v[128:131], v[200:203], v[52:55]
	v_mfma_f32_16x16x32_bf16 v[60:63], v[132:135], v[200:203], v[60:63]
	v_mfma_f32_16x16x32_bf16 v[20:23], v[136:139], v[200:203], v[20:23]
	v_mfma_f32_16x16x32_bf16 v[28:31], v[140:143], v[200:203], v[28:31]
	s_waitcnt lgkmcnt(1)
	v_mfma_f32_16x16x32_bf16 v[32:35], v[128:131], v[204:207], v[32:35]
	v_mfma_f32_16x16x32_bf16 v[40:43], v[132:135], v[204:207], v[40:43]
	v_mfma_f32_16x16x32_bf16 v[0:3], v[136:139], v[204:207], v[0:3]
	v_mfma_f32_16x16x32_bf16 v[8:11], v[140:143], v[204:207], v[8:11]
	s_waitcnt lgkmcnt(0)
	v_mfma_f32_16x16x32_bf16 v[36:39], v[128:131], v[242:245], v[36:39]
	v_mfma_f32_16x16x32_bf16 v[44:47], v[132:135], v[242:245], v[44:47]
	v_mfma_f32_16x16x32_bf16 v[4:7], v[136:139], v[242:245], v[4:7]
	v_mfma_f32_16x16x32_bf16 v[12:15], v[140:143], v[242:245], v[12:15]
	s_waitcnt vmcnt(4)
	s_barrier
	ds_read_b128 v[196:199], v246 offset:8192
	ds_read_b128 v[200:203], v246 offset:9216
	ds_read_b128 v[204:207], v246 offset:10240
	ds_read_b128 v[242:245], v246 offset:11264
	s_waitcnt vmcnt(0) lgkmcnt(3)
	v_mfma_f32_16x16x32_bf16 v[112:115], v[144:147], v[196:199], v[112:115]
	v_mfma_f32_16x16x32_bf16 v[120:123], v[148:151], v[196:199], v[120:123]
	v_mfma_f32_16x16x32_bf16 v[80:83], v[152:155], v[196:199], v[80:83]
	v_mfma_f32_16x16x32_bf16 v[88:91], v[156:159], v[196:199], v[88:91]
	ds_read_b128 v[196:199], v246 offset:12288
	s_waitcnt lgkmcnt(3)
	v_mfma_f32_16x16x32_bf16 v[116:119], v[144:147], v[200:203], v[116:119]
	v_mfma_f32_16x16x32_bf16 v[124:127], v[148:151], v[200:203], v[124:127]
	v_mfma_f32_16x16x32_bf16 v[84:87], v[152:155], v[200:203], v[84:87]
	v_mfma_f32_16x16x32_bf16 v[92:95], v[156:159], v[200:203], v[92:95]
	ds_read_b128 v[200:203], v246 offset:13312
	s_waitcnt lgkmcnt(3)
	v_mfma_f32_16x16x32_bf16 v[96:99], v[144:147], v[204:207], v[96:99]
	v_mfma_f32_16x16x32_bf16 v[104:107], v[148:151], v[204:207], v[104:107]
	v_mfma_f32_16x16x32_bf16 v[64:67], v[152:155], v[204:207], v[64:67]
	v_mfma_f32_16x16x32_bf16 v[72:75], v[156:159], v[204:207], v[72:75]
	ds_read_b128 v[204:207], v246 offset:14336
	s_waitcnt lgkmcnt(3)
	v_mfma_f32_16x16x32_bf16 v[100:103], v[144:147], v[242:245], v[100:103]
	v_mfma_f32_16x16x32_bf16 v[108:111], v[148:151], v[242:245], v[108:111]
	v_mfma_f32_16x16x32_bf16 v[68:71], v[152:155], v[242:245], v[68:71]
	v_mfma_f32_16x16x32_bf16 v[76:79], v[156:159], v[242:245], v[76:79]
	ds_read_b128 v[242:245], v246 offset:15360
	v_permlane16_swap_b32_e32 v112, v116
	v_permlane16_swap_b32_e32 v113, v117
	v_permlane16_swap_b32_e32 v114, v118
	v_permlane16_swap_b32_e32 v115, v119
	v_permlane16_swap_b32_e32 v120, v124
	v_permlane16_swap_b32_e32 v121, v125
	v_permlane16_swap_b32_e32 v122, v126
	v_permlane16_swap_b32_e32 v123, v127
	v_permlane16_swap_b32_e32 v80, v84
	v_permlane16_swap_b32_e32 v81, v85
	v_permlane16_swap_b32_e32 v82, v86
	v_permlane16_swap_b32_e32 v83, v87
	v_permlane16_swap_b32_e32 v88, v92
	v_permlane16_swap_b32_e32 v89, v93
	v_permlane16_swap_b32_e32 v90, v94
	v_permlane16_swap_b32_e32 v91, v95
	v_permlane32_swap_b32_e32 v112, v116
	v_permlane32_swap_b32_e32 v113, v117
	v_permlane32_swap_b32_e32 v114, v118
	v_permlane32_swap_b32_e32 v115, v119
	v_permlane32_swap_b32_e32 v120, v124
	v_permlane32_swap_b32_e32 v121, v125
	v_permlane32_swap_b32_e32 v122, v126
	v_permlane32_swap_b32_e32 v123, v127
	v_permlane32_swap_b32_e32 v80, v84
	v_permlane32_swap_b32_e32 v81, v85
	v_permlane32_swap_b32_e32 v82, v86
	v_permlane32_swap_b32_e32 v83, v87
	v_permlane32_swap_b32_e32 v88, v92
	v_permlane32_swap_b32_e32 v89, v93
	v_permlane32_swap_b32_e32 v90, v94
	v_permlane32_swap_b32_e32 v91, v95
	s_waitcnt lgkmcnt(3)
	v_mfma_f32_16x16x32_bf16 v[48:51], v[144:147], v[196:199], v[48:51]
	v_mfma_f32_16x16x32_bf16 v[56:59], v[148:151], v[196:199], v[56:59]
	v_mfma_f32_16x16x32_bf16 v[16:19], v[152:155], v[196:199], v[16:19]
	v_mfma_f32_16x16x32_bf16 v[24:27], v[156:159], v[196:199], v[24:27]
	s_waitcnt lgkmcnt(2)
	v_mfma_f32_16x16x32_bf16 v[52:55], v[144:147], v[200:203], v[52:55]
	v_mfma_f32_16x16x32_bf16 v[60:63], v[148:151], v[200:203], v[60:63]
	v_mfma_f32_16x16x32_bf16 v[20:23], v[152:155], v[200:203], v[20:23]
	v_mfma_f32_16x16x32_bf16 v[28:31], v[156:159], v[200:203], v[28:31]
	v_permlane16_swap_b32_e32 v96, v100
	v_permlane16_swap_b32_e32 v97, v101
	v_permlane16_swap_b32_e32 v98, v102
	v_permlane16_swap_b32_e32 v99, v103
	v_permlane16_swap_b32_e32 v104, v108
	v_permlane16_swap_b32_e32 v105, v109
	v_permlane16_swap_b32_e32 v106, v110
	v_permlane16_swap_b32_e32 v107, v111
	v_permlane16_swap_b32_e32 v64, v68
	v_permlane16_swap_b32_e32 v65, v69
	v_permlane16_swap_b32_e32 v66, v70
	v_permlane16_swap_b32_e32 v67, v71
	v_permlane16_swap_b32_e32 v72, v76
	v_permlane16_swap_b32_e32 v73, v77
	v_permlane16_swap_b32_e32 v74, v78
	v_permlane16_swap_b32_e32 v75, v79
	v_permlane32_swap_b32_e32 v96, v100
	v_permlane32_swap_b32_e32 v97, v101
	v_permlane32_swap_b32_e32 v98, v102
	v_permlane32_swap_b32_e32 v99, v103
	v_permlane32_swap_b32_e32 v104, v108
	v_permlane32_swap_b32_e32 v105, v109
	v_permlane32_swap_b32_e32 v106, v110
	v_permlane32_swap_b32_e32 v107, v111
	v_permlane32_swap_b32_e32 v64, v68
	v_permlane32_swap_b32_e32 v65, v69
	v_permlane32_swap_b32_e32 v66, v70
	v_permlane32_swap_b32_e32 v67, v71
	v_permlane32_swap_b32_e32 v72, v76
	v_permlane32_swap_b32_e32 v73, v77
	v_permlane32_swap_b32_e32 v74, v78
	v_permlane32_swap_b32_e32 v75, v79
	s_waitcnt lgkmcnt(1)
	v_mfma_f32_16x16x32_bf16 v[32:35], v[144:147], v[204:207], v[32:35]
	v_mfma_f32_16x16x32_bf16 v[40:43], v[148:151], v[204:207], v[40:43]
	v_mfma_f32_16x16x32_bf16 v[0:3], v[152:155], v[204:207], v[0:3]
	v_mfma_f32_16x16x32_bf16 v[8:11], v[156:159], v[204:207], v[8:11]
	s_waitcnt lgkmcnt(0)
	v_mfma_f32_16x16x32_bf16 v[36:39], v[144:147], v[242:245], v[36:39]
	v_mfma_f32_16x16x32_bf16 v[44:47], v[148:151], v[242:245], v[44:47]
	v_mfma_f32_16x16x32_bf16 v[4:7], v[152:155], v[242:245], v[4:7]
	v_mfma_f32_16x16x32_bf16 v[12:15], v[156:159], v[242:245], v[12:15]
	v_permlane16_swap_b32_e32 v48, v52
	v_permlane16_swap_b32_e32 v49, v53
	v_permlane16_swap_b32_e32 v50, v54
	v_permlane16_swap_b32_e32 v51, v55
	v_permlane16_swap_b32_e32 v56, v60
	v_permlane16_swap_b32_e32 v57, v61
	v_permlane16_swap_b32_e32 v58, v62
	v_permlane16_swap_b32_e32 v59, v63
	v_permlane16_swap_b32_e32 v16, v20
	v_permlane16_swap_b32_e32 v17, v21
	v_permlane16_swap_b32_e32 v18, v22
	v_permlane16_swap_b32_e32 v19, v23
	v_permlane16_swap_b32_e32 v24, v28
	v_permlane16_swap_b32_e32 v25, v29
	v_permlane16_swap_b32_e32 v26, v30
	v_permlane16_swap_b32_e32 v27, v31
	v_permlane32_swap_b32_e32 v48, v52
	v_permlane32_swap_b32_e32 v49, v53
	v_permlane32_swap_b32_e32 v50, v54
	v_permlane32_swap_b32_e32 v51, v55
	v_permlane32_swap_b32_e32 v56, v60
	v_permlane32_swap_b32_e32 v57, v61
	v_permlane32_swap_b32_e32 v58, v62
	v_permlane32_swap_b32_e32 v59, v63
	v_permlane32_swap_b32_e32 v16, v20
	v_permlane32_swap_b32_e32 v17, v21
	v_permlane32_swap_b32_e32 v18, v22
	v_permlane32_swap_b32_e32 v19, v23
	v_permlane32_swap_b32_e32 v24, v28
	v_permlane32_swap_b32_e32 v25, v29
	v_permlane32_swap_b32_e32 v26, v30
	v_permlane32_swap_b32_e32 v27, v31
	s_barrier
	s_nop 7
	v_permlane16_swap_b32_e32 v32, v36
	v_permlane16_swap_b32_e32 v33, v37
	v_permlane16_swap_b32_e32 v34, v38
	v_permlane16_swap_b32_e32 v35, v39
	v_permlane16_swap_b32_e32 v40, v44
	v_permlane16_swap_b32_e32 v41, v45
	v_permlane16_swap_b32_e32 v42, v46
	v_permlane16_swap_b32_e32 v43, v47
	v_permlane16_swap_b32_e32 v0, v4
	v_permlane16_swap_b32_e32 v1, v5
	v_permlane16_swap_b32_e32 v2, v6
	v_permlane16_swap_b32_e32 v3, v7
	v_permlane16_swap_b32_e32 v8, v12
	v_permlane16_swap_b32_e32 v9, v13
	v_permlane16_swap_b32_e32 v10, v14
	v_permlane16_swap_b32_e32 v11, v15
	v_permlane32_swap_b32_e32 v32, v36
	v_permlane32_swap_b32_e32 v33, v37
	v_permlane32_swap_b32_e32 v34, v38
	v_permlane32_swap_b32_e32 v35, v39
	v_permlane32_swap_b32_e32 v40, v44
	v_permlane32_swap_b32_e32 v41, v45
	v_permlane32_swap_b32_e32 v42, v46
	v_permlane32_swap_b32_e32 v43, v47
	v_permlane32_swap_b32_e32 v0, v4
	v_permlane32_swap_b32_e32 v1, v5
	v_permlane32_swap_b32_e32 v2, v6
	v_permlane32_swap_b32_e32 v3, v7
	v_permlane32_swap_b32_e32 v8, v12
	v_permlane32_swap_b32_e32 v9, v13
	v_permlane32_swap_b32_e32 v10, v14
	v_permlane32_swap_b32_e32 v11, v15
	s_waitcnt vmcnt(0)
	s_waitcnt vmcnt(0)
	v_mul_f32_e32 v133, 0xbfb8aa3b, v112
	v_exp_f32_e32 v133, v133
	s_movk_i32 s1, 0x2400
	v_mul_lo_u32 v128, v238, s1
	v_lshl_or_b32 v131, s0, 6, v181
	v_add_f32_e32 v133, 1.0, v133
	v_lshl_or_b32 v132, v239, 1, v128
	v_and_b32_e32 v129, 0xffffffc0, v237
	v_lshl_or_b32 v128, v181, 1, v128
	v_rcp_f32_e32 v135, v133
	s_nop 0
	v_mul_f32_e32 v112, v112, v135
	v_mul_f32_e32 v96, v96, v112
	v_cvt_pk_bf16_f32 v112, v96, s0
	s_movk_i32 s0, 0x240
	v_mad_u32_u24 v96, v183, s0, v132
	ds_write_b16 v96, v112
	v_mul_f32_e32 v112, 0xbfb8aa3b, v113
	v_exp_f32_e32 v112, v112
	v_lshl_add_u32 v130, s7, 8, v129
	v_lshrrev_b32_e32 v129, 2, v240
	v_mad_u32_u24 v128, v129, s42, v128
	v_add_f32_e32 v112, 1.0, v112
	v_rcp_f32_e32 v133, v112
	s_nop 0
	v_mul_f32_e32 v112, v113, v133
	v_mul_f32_e32 v97, v97, v112
	v_cvt_pk_bf16_f32 v97, v97, s0
	ds_write_b16 v96, v97 offset:144
	v_mul_f32_e32 v136, 0xbfb8aa3b, v114
	v_mul_f32_e32 v137, 0xbfb8aa3b, v115
	v_mul_f32_e32 v138, 0xbfb8aa3b, v116
	v_mul_f32_e32 v139, 0xbfb8aa3b, v117
	v_mul_f32_e32 v140, 0xbfb8aa3b, v118
	v_mul_f32_e32 v141, 0xbfb8aa3b, v119
	v_mul_f32_e32 v142, 0xbfb8aa3b, v120
	v_mul_f32_e32 v143, 0xbfb8aa3b, v121
	v_exp_f32_e32 v136, v136
	v_exp_f32_e32 v137, v137
	v_exp_f32_e32 v138, v138
	v_exp_f32_e32 v139, v139
	v_exp_f32_e32 v140, v140
	v_exp_f32_e32 v141, v141
	v_exp_f32_e32 v142, v142
	v_exp_f32_e32 v143, v143
	v_add_f32_e32 v136, 1.0, v136
	v_add_f32_e32 v137, 1.0, v137
	v_add_f32_e32 v138, 1.0, v138
	v_add_f32_e32 v139, 1.0, v139
	v_add_f32_e32 v140, 1.0, v140
	v_add_f32_e32 v141, 1.0, v141
	v_add_f32_e32 v142, 1.0, v142
	v_add_f32_e32 v143, 1.0, v143
	v_rcp_f32_e32 v136, v136
	v_rcp_f32_e32 v137, v137
	v_rcp_f32_e32 v138, v138
	v_rcp_f32_e32 v139, v139
	v_rcp_f32_e32 v140, v140
	v_rcp_f32_e32 v141, v141
	v_rcp_f32_e32 v142, v142
	v_rcp_f32_e32 v143, v143
	v_mul_f32_e32 v136, v114, v136
	v_mul_f32_e32 v137, v115, v137
	v_mul_f32_e32 v138, v116, v138
	v_mul_f32_e32 v139, v117, v139
	v_mul_f32_e32 v140, v118, v140
	v_mul_f32_e32 v141, v119, v141
	v_mul_f32_e32 v142, v120, v142
	v_mul_f32_e32 v143, v121, v143
	v_mul_f32_e32 v136, v98, v136
	v_mul_f32_e32 v137, v99, v137
	v_mul_f32_e32 v138, v100, v138
	v_mul_f32_e32 v139, v101, v139
	v_mul_f32_e32 v140, v102, v140
	v_mul_f32_e32 v141, v103, v141
	v_mul_f32_e32 v142, v104, v142
	v_mul_f32_e32 v143, v105, v143
	v_cvt_pk_bf16_f32 v136, v136, s0
	v_cvt_pk_bf16_f32 v137, v137, s0
	v_cvt_pk_bf16_f32 v138, v138, s0
	v_cvt_pk_bf16_f32 v139, v139, s0
	v_cvt_pk_bf16_f32 v140, v140, s0
	v_cvt_pk_bf16_f32 v141, v141, s0
	v_cvt_pk_bf16_f32 v142, v142, s0
	v_cvt_pk_bf16_f32 v143, v143, s0
	ds_write_b16 v96, v136 offset:288
	ds_write_b16 v96, v137 offset:432
	ds_write_b16 v96, v138 offset:1152
	ds_write_b16 v96, v139 offset:1296
	ds_write_b16 v96, v140 offset:1440
	ds_write_b16 v96, v141 offset:1584
	ds_write_b16 v96, v142 offset:2304
	ds_write_b16 v96, v143 offset:2448
	v_mul_f32_e32 v136, 0xbfb8aa3b, v122
	v_mul_f32_e32 v137, 0xbfb8aa3b, v123
	v_mul_f32_e32 v138, 0xbfb8aa3b, v124
	v_mul_f32_e32 v139, 0xbfb8aa3b, v125
	v_mul_f32_e32 v140, 0xbfb8aa3b, v126
	v_mul_f32_e32 v141, 0xbfb8aa3b, v127
	v_mul_f32_e32 v142, 0xbfb8aa3b, v80
	v_mul_f32_e32 v143, 0xbfb8aa3b, v81
	v_exp_f32_e32 v136, v136
	v_exp_f32_e32 v137, v137
	v_exp_f32_e32 v138, v138
	v_exp_f32_e32 v139, v139
	v_exp_f32_e32 v140, v140
	v_exp_f32_e32 v141, v141
	v_exp_f32_e32 v142, v142
	v_exp_f32_e32 v143, v143
	v_add_f32_e32 v136, 1.0, v136
	v_add_f32_e32 v137, 1.0, v137
	v_add_f32_e32 v138, 1.0, v138
	v_add_f32_e32 v139, 1.0, v139
	v_add_f32_e32 v140, 1.0, v140
	v_add_f32_e32 v141, 1.0, v141
	v_add_f32_e32 v142, 1.0, v142
	v_add_f32_e32 v143, 1.0, v143
	v_rcp_f32_e32 v136, v136
	v_rcp_f32_e32 v137, v137
	v_rcp_f32_e32 v138, v138
	v_rcp_f32_e32 v139, v139
	v_rcp_f32_e32 v140, v140
	v_rcp_f32_e32 v141, v141
	v_rcp_f32_e32 v142, v142
	v_rcp_f32_e32 v143, v143
	v_mul_f32_e32 v136, v122, v136
	v_mul_f32_e32 v137, v123, v137
	v_mul_f32_e32 v138, v124, v138
	v_mul_f32_e32 v139, v125, v139
	v_mul_f32_e32 v140, v126, v140
	v_mul_f32_e32 v141, v127, v141
	v_mul_f32_e32 v142, v80, v142
	v_mul_f32_e32 v143, v81, v143
	v_mul_f32_e32 v136, v106, v136
	v_mul_f32_e32 v137, v107, v137
	v_mul_f32_e32 v138, v108, v138
	v_mul_f32_e32 v139, v109, v139
	v_mul_f32_e32 v140, v110, v140
	v_mul_f32_e32 v141, v111, v141
	v_mul_f32_e32 v142, v64, v142
	v_mul_f32_e32 v143, v65, v143
	v_cvt_pk_bf16_f32 v136, v136, s0
	v_cvt_pk_bf16_f32 v137, v137, s0
	v_cvt_pk_bf16_f32 v138, v138, s0
	v_cvt_pk_bf16_f32 v139, v139, s0
	v_cvt_pk_bf16_f32 v140, v140, s0
	v_cvt_pk_bf16_f32 v141, v141, s0
	v_cvt_pk_bf16_f32 v142, v142, s0
	v_cvt_pk_bf16_f32 v143, v143, s0
	ds_write_b16 v96, v136 offset:2592
	ds_write_b16 v96, v137 offset:2736
	ds_write_b16 v96, v138 offset:3456
	ds_write_b16 v96, v139 offset:3600
	ds_write_b16 v96, v140 offset:3744
	ds_write_b16 v96, v141 offset:3888
	ds_write_b16 v96, v142 offset:4608
	ds_write_b16 v96, v143 offset:4752
	v_mul_f32_e32 v136, 0xbfb8aa3b, v82
	v_mul_f32_e32 v137, 0xbfb8aa3b, v83
	v_mul_f32_e32 v138, 0xbfb8aa3b, v84
	v_mul_f32_e32 v139, 0xbfb8aa3b, v85
	v_mul_f32_e32 v140, 0xbfb8aa3b, v86
	v_mul_f32_e32 v141, 0xbfb8aa3b, v87
	v_exp_f32_e32 v136, v136
	v_exp_f32_e32 v137, v137
	v_exp_f32_e32 v138, v138
	v_exp_f32_e32 v139, v139
	v_exp_f32_e32 v140, v140
	v_exp_f32_e32 v141, v141
	v_add_f32_e32 v136, 1.0, v136
	v_add_f32_e32 v137, 1.0, v137
	v_add_f32_e32 v138, 1.0, v138
	v_add_f32_e32 v139, 1.0, v139
	v_add_f32_e32 v140, 1.0, v140
	v_add_f32_e32 v141, 1.0, v141
	v_rcp_f32_e32 v136, v136
	v_rcp_f32_e32 v137, v137
	v_rcp_f32_e32 v138, v138
	v_rcp_f32_e32 v139, v139
	v_rcp_f32_e32 v140, v140
	v_rcp_f32_e32 v141, v141
	v_mul_f32_e32 v136, v82, v136
	v_mul_f32_e32 v137, v83, v137
	v_mul_f32_e32 v138, v84, v138
	v_mul_f32_e32 v139, v85, v139
	v_mul_f32_e32 v140, v86, v140
	v_mul_f32_e32 v141, v87, v141
	v_mul_f32_e32 v136, v66, v136
	v_mul_f32_e32 v137, v67, v137
	v_mul_f32_e32 v138, v68, v138
	v_mul_f32_e32 v139, v69, v139
	v_mul_f32_e32 v140, v70, v140
	v_mul_f32_e32 v141, v71, v141
	v_cvt_pk_bf16_f32 v136, v136, s0
	v_cvt_pk_bf16_f32 v137, v137, s0
	v_cvt_pk_bf16_f32 v138, v138, s0
	v_cvt_pk_bf16_f32 v139, v139, s0
	v_cvt_pk_bf16_f32 v140, v140, s0
	v_cvt_pk_bf16_f32 v141, v141, s0
	ds_write_b16 v96, v136 offset:4896
	ds_write_b16 v96, v137 offset:5040
	ds_write_b16 v96, v138 offset:5760
	ds_write_b16 v96, v139 offset:5904
	ds_write_b16 v96, v140 offset:6048
	ds_write_b16 v96, v141 offset:6192
	v_mul_f32_e32 v64, 0xbfb8aa3b, v88
	v_exp_f32_e32 v64, v64
	v_ashrrev_i32_e32 v71, 5, v130
	v_or_b32_e32 v70, 1, v71
	v_add_f32_e32 v64, 1.0, v64
	v_rcp_f32_e32 v66, v64
	s_nop 0
	v_mul_f32_e32 v64, v88, v66
	v_mul_f32_e32 v64, v72, v64
	v_cvt_pk_bf16_f32 v64, v64, s0
	ds_write_b16 v96, v64 offset:6912
	v_mul_f32_e32 v136, 0xbfb8aa3b, v89
	v_mul_f32_e32 v137, 0xbfb8aa3b, v90
	v_mul_f32_e32 v138, 0xbfb8aa3b, v91
	v_mul_f32_e32 v139, 0xbfb8aa3b, v92
	v_mul_f32_e32 v140, 0xbfb8aa3b, v93
	v_mul_f32_e32 v141, 0xbfb8aa3b, v94
	v_mul_f32_e32 v142, 0xbfb8aa3b, v95
	v_exp_f32_e32 v136, v136
	v_exp_f32_e32 v137, v137
	v_exp_f32_e32 v138, v138
	v_exp_f32_e32 v139, v139
	v_exp_f32_e32 v140, v140
	v_exp_f32_e32 v141, v141
	v_exp_f32_e32 v142, v142
	v_add_f32_e32 v136, 1.0, v136
	v_add_f32_e32 v137, 1.0, v137
	v_add_f32_e32 v138, 1.0, v138
	v_add_f32_e32 v139, 1.0, v139
	v_add_f32_e32 v140, 1.0, v140
	v_add_f32_e32 v141, 1.0, v141
	v_add_f32_e32 v142, 1.0, v142
	v_rcp_f32_e32 v136, v136
	v_rcp_f32_e32 v137, v137
	v_rcp_f32_e32 v138, v138
	v_rcp_f32_e32 v139, v139
	v_rcp_f32_e32 v140, v140
	v_rcp_f32_e32 v141, v141
	v_rcp_f32_e32 v142, v142
	v_mul_f32_e32 v136, v89, v136
	v_mul_f32_e32 v137, v90, v137
	v_mul_f32_e32 v138, v91, v138
	v_mul_f32_e32 v139, v92, v139
	v_mul_f32_e32 v140, v93, v140
	v_mul_f32_e32 v141, v94, v141
	v_mul_f32_e32 v142, v95, v142
	v_mul_f32_e32 v136, v73, v136
	v_mul_f32_e32 v137, v74, v137
	v_mul_f32_e32 v138, v75, v138
	v_mul_f32_e32 v139, v76, v139
	v_mul_f32_e32 v140, v77, v140
	v_mul_f32_e32 v141, v78, v141
	v_mul_f32_e32 v142, v79, v142
	v_cvt_pk_bf16_f32 v136, v136, s0
	v_cvt_pk_bf16_f32 v137, v137, s0
	v_cvt_pk_bf16_f32 v138, v138, s0
	v_cvt_pk_bf16_f32 v139, v139, s0
	v_cvt_pk_bf16_f32 v140, v140, s0
	v_cvt_pk_bf16_f32 v141, v141, s0
	v_cvt_pk_bf16_f32 v142, v142, s0
	ds_write_b16 v96, v136 offset:7056
	ds_write_b16 v96, v137 offset:7200
	ds_write_b16 v96, v138 offset:7344
	ds_write_b16 v96, v139 offset:8064
	ds_write_b16 v96, v140 offset:8208
	ds_write_b16 v96, v141 offset:8352
	ds_write_b16 v96, v142 offset:8496
	v_ashrrev_i32_e32 v68, 4, v131
	s_waitcnt lgkmcnt(0)
	v_ashrrev_i32_e32 v69, 31, v68
	ds_read_b128 v[72:75], v128
	v_mad_i64_i32 v[64:65], s[0:1], v71, s23, v[68:69]
	v_lshlrev_b64 v[64:65], 10, v[64:65]
	v_lshlrev_b32_e32 v66, 6, v181
	v_lshl_add_u64 v[64:65], s[66:67], 0, v[64:65]
	v_and_b32_e32 v176, 0x200, v66
	v_lshl_add_u64 v[76:77], v[64:65], 0, v[176:177]
	v_lshlrev_b32_e32 v66, 4, v129
	v_mov_b32_e32 v67, v177
	v_lshl_add_u64 v[64:65], v[76:77], 0, v[66:67]
	s_waitcnt lgkmcnt(0)
	global_store_dwordx4 v[64:65], v[72:75], off
	ds_read_b128 v[72:75], v128 offset:2304
	v_or_b32_e32 v64, 0x100, v66
	v_mov_b32_e32 v65, v177
	v_lshl_add_u64 v[76:77], v[76:77], 0, v[64:65]
	s_waitcnt lgkmcnt(0)
	global_store_dwordx4 v[76:77], v[72:75], off
	ds_read_b128 v[72:75], v128 offset:4608
	v_mad_i64_i32 v[76:77], s[0:1], v70, s23, v[68:69]
	v_lshlrev_b64 v[76:77], 10, v[76:77]
	v_lshl_add_u64 v[76:77], s[66:67], 0, v[76:77]
	v_lshl_add_u64 v[76:77], v[76:77], 0, v[176:177]
	v_lshl_add_u64 v[78:79], v[76:77], 0, v[66:67]
	v_mul_f32_e32 v69, 0xbfb8aa3b, v48
	s_waitcnt lgkmcnt(0)
	global_store_dwordx4 v[78:79], v[72:75], off
	ds_read_b128 v[72:75], v128 offset:6912
	v_exp_f32_e32 v69, v69
	v_lshl_add_u64 v[76:77], v[76:77], 0, v[64:65]
	v_add_f32_e32 v69, 1.0, v69
	s_waitcnt lgkmcnt(0)
	global_store_dwordx4 v[76:77], v[72:75], off
	s_waitcnt lgkmcnt(0)
	s_nop 1
	v_rcp_f32_e32 v73, v69
	s_nop 0
	v_mul_f32_e32 v48, v48, v73
	v_mul_f32_e32 v32, v32, v48
	v_cvt_pk_bf16_f32 v32, v32, s0
	ds_write_b16 v96, v32
	v_mul_f32_e32 v136, 0xbfb8aa3b, v49
	v_mul_f32_e32 v137, 0xbfb8aa3b, v50
	v_mul_f32_e32 v138, 0xbfb8aa3b, v51
	v_mul_f32_e32 v139, 0xbfb8aa3b, v52
	v_mul_f32_e32 v140, 0xbfb8aa3b, v53
	v_mul_f32_e32 v141, 0xbfb8aa3b, v54
	v_mul_f32_e32 v142, 0xbfb8aa3b, v55
	v_mul_f32_e32 v143, 0xbfb8aa3b, v56
	v_exp_f32_e32 v136, v136
	v_exp_f32_e32 v137, v137
	v_exp_f32_e32 v138, v138
	v_exp_f32_e32 v139, v139
	v_exp_f32_e32 v140, v140
	v_exp_f32_e32 v141, v141
	v_exp_f32_e32 v142, v142
	v_exp_f32_e32 v143, v143
	v_add_f32_e32 v136, 1.0, v136
	v_add_f32_e32 v137, 1.0, v137
	v_add_f32_e32 v138, 1.0, v138
	v_add_f32_e32 v139, 1.0, v139
	v_add_f32_e32 v140, 1.0, v140
	v_add_f32_e32 v141, 1.0, v141
	v_add_f32_e32 v142, 1.0, v142
	v_add_f32_e32 v143, 1.0, v143
	v_rcp_f32_e32 v136, v136
	v_rcp_f32_e32 v137, v137
	v_rcp_f32_e32 v138, v138
	v_rcp_f32_e32 v139, v139
	v_rcp_f32_e32 v140, v140
	v_rcp_f32_e32 v141, v141
	v_rcp_f32_e32 v142, v142
	v_rcp_f32_e32 v143, v143
	v_mul_f32_e32 v136, v49, v136
	v_mul_f32_e32 v137, v50, v137
	v_mul_f32_e32 v138, v51, v138
	v_mul_f32_e32 v139, v52, v139
	v_mul_f32_e32 v140, v53, v140
	v_mul_f32_e32 v141, v54, v141
	v_mul_f32_e32 v142, v55, v142
	v_mul_f32_e32 v143, v56, v143
	v_mul_f32_e32 v136, v33, v136
	v_mul_f32_e32 v137, v34, v137
	v_mul_f32_e32 v138, v35, v138
	v_mul_f32_e32 v139, v36, v139
	v_mul_f32_e32 v140, v37, v140
	v_mul_f32_e32 v141, v38, v141
	v_mul_f32_e32 v142, v39, v142
	v_mul_f32_e32 v143, v40, v143
	v_cvt_pk_bf16_f32 v136, v136, s0
	v_cvt_pk_bf16_f32 v137, v137, s0
	v_cvt_pk_bf16_f32 v138, v138, s0
	v_cvt_pk_bf16_f32 v139, v139, s0
	v_cvt_pk_bf16_f32 v140, v140, s0
	v_cvt_pk_bf16_f32 v141, v141, s0
	v_cvt_pk_bf16_f32 v142, v142, s0
	v_cvt_pk_bf16_f32 v143, v143, s0
	ds_write_b16 v96, v136 offset:144
	ds_write_b16 v96, v137 offset:288
	ds_write_b16 v96, v138 offset:432
	ds_write_b16 v96, v139 offset:1152
	ds_write_b16 v96, v140 offset:1296
	ds_write_b16 v96, v141 offset:1440
	ds_write_b16 v96, v142 offset:1584
	ds_write_b16 v96, v143 offset:2304
	v_mul_f32_e32 v136, 0xbfb8aa3b, v57
	v_mul_f32_e32 v137, 0xbfb8aa3b, v58
	v_mul_f32_e32 v138, 0xbfb8aa3b, v59
	v_mul_f32_e32 v139, 0xbfb8aa3b, v60
	v_mul_f32_e32 v140, 0xbfb8aa3b, v61
	v_mul_f32_e32 v141, 0xbfb8aa3b, v62
	v_mul_f32_e32 v142, 0xbfb8aa3b, v63
	v_mul_f32_e32 v143, 0xbfb8aa3b, v16
	v_exp_f32_e32 v136, v136
	v_exp_f32_e32 v137, v137
	v_exp_f32_e32 v138, v138
	v_exp_f32_e32 v139, v139
	v_exp_f32_e32 v140, v140
	v_exp_f32_e32 v141, v141
	v_exp_f32_e32 v142, v142
	v_exp_f32_e32 v143, v143
	v_add_f32_e32 v136, 1.0, v136
	v_add_f32_e32 v137, 1.0, v137
	v_add_f32_e32 v138, 1.0, v138
	v_add_f32_e32 v139, 1.0, v139
	v_add_f32_e32 v140, 1.0, v140
	v_add_f32_e32 v141, 1.0, v141
	v_add_f32_e32 v142, 1.0, v142
	v_add_f32_e32 v143, 1.0, v143
	v_rcp_f32_e32 v136, v136
	v_rcp_f32_e32 v137, v137
	v_rcp_f32_e32 v138, v138
	v_rcp_f32_e32 v139, v139
	v_rcp_f32_e32 v140, v140
	v_rcp_f32_e32 v141, v141
	v_rcp_f32_e32 v142, v142
	v_rcp_f32_e32 v143, v143
	v_mul_f32_e32 v136, v57, v136
	v_mul_f32_e32 v137, v58, v137
	v_mul_f32_e32 v138, v59, v138
	v_mul_f32_e32 v139, v60, v139
	v_mul_f32_e32 v140, v61, v140
	v_mul_f32_e32 v141, v62, v141
	v_mul_f32_e32 v142, v63, v142
	v_mul_f32_e32 v143, v16, v143
	v_mul_f32_e32 v136, v41, v136
	v_mul_f32_e32 v137, v42, v137
	v_mul_f32_e32 v138, v43, v138
	v_mul_f32_e32 v139, v44, v139
	v_mul_f32_e32 v140, v45, v140
	v_mul_f32_e32 v141, v46, v141
	v_mul_f32_e32 v142, v47, v142
	v_mul_f32_e32 v143, v0, v143
	v_cvt_pk_bf16_f32 v136, v136, s0
	v_cvt_pk_bf16_f32 v137, v137, s0
	v_cvt_pk_bf16_f32 v138, v138, s0
	v_cvt_pk_bf16_f32 v139, v139, s0
	v_cvt_pk_bf16_f32 v140, v140, s0
	v_cvt_pk_bf16_f32 v141, v141, s0
	v_cvt_pk_bf16_f32 v142, v142, s0
	v_cvt_pk_bf16_f32 v143, v143, s0
	ds_write_b16 v96, v136 offset:2448
	ds_write_b16 v96, v137 offset:2592
	ds_write_b16 v96, v138 offset:2736
	ds_write_b16 v96, v139 offset:3456
	ds_write_b16 v96, v140 offset:3600
	ds_write_b16 v96, v141 offset:3744
	ds_write_b16 v96, v142 offset:3888
	ds_write_b16 v96, v143 offset:4608
	v_mul_f32_e32 v136, 0xbfb8aa3b, v17
	v_mul_f32_e32 v137, 0xbfb8aa3b, v18
	v_mul_f32_e32 v138, 0xbfb8aa3b, v19
	v_mul_f32_e32 v139, 0xbfb8aa3b, v20
	v_mul_f32_e32 v140, 0xbfb8aa3b, v21
	v_mul_f32_e32 v141, 0xbfb8aa3b, v22
	v_mul_f32_e32 v142, 0xbfb8aa3b, v23
	v_mul_f32_e32 v143, 0xbfb8aa3b, v24
	v_exp_f32_e32 v136, v136
	v_exp_f32_e32 v137, v137
	v_exp_f32_e32 v138, v138
	v_exp_f32_e32 v139, v139
	v_exp_f32_e32 v140, v140
	v_exp_f32_e32 v141, v141
	v_exp_f32_e32 v142, v142
	v_exp_f32_e32 v143, v143
	v_add_f32_e32 v136, 1.0, v136
	v_add_f32_e32 v137, 1.0, v137
	v_add_f32_e32 v138, 1.0, v138
	v_add_f32_e32 v139, 1.0, v139
	v_add_f32_e32 v140, 1.0, v140
	v_add_f32_e32 v141, 1.0, v141
	v_add_f32_e32 v142, 1.0, v142
	v_add_f32_e32 v143, 1.0, v143
	v_rcp_f32_e32 v136, v136
	v_rcp_f32_e32 v137, v137
	v_rcp_f32_e32 v138, v138
	v_rcp_f32_e32 v139, v139
	v_rcp_f32_e32 v140, v140
	v_rcp_f32_e32 v141, v141
	v_rcp_f32_e32 v142, v142
	v_rcp_f32_e32 v143, v143
	v_mul_f32_e32 v136, v17, v136
	v_mul_f32_e32 v137, v18, v137
	v_mul_f32_e32 v138, v19, v138
	v_mul_f32_e32 v139, v20, v139
	v_mul_f32_e32 v140, v21, v140
	v_mul_f32_e32 v141, v22, v141
	v_mul_f32_e32 v142, v23, v142
	v_mul_f32_e32 v143, v24, v143
	v_mul_f32_e32 v136, v1, v136
	v_mul_f32_e32 v137, v2, v137
	v_mul_f32_e32 v138, v3, v138
	v_mul_f32_e32 v139, v4, v139
	v_mul_f32_e32 v140, v5, v140
	v_mul_f32_e32 v141, v6, v141
	v_mul_f32_e32 v142, v7, v142
	v_mul_f32_e32 v143, v8, v143
	v_cvt_pk_bf16_f32 v136, v136, s0
	v_cvt_pk_bf16_f32 v137, v137, s0
	v_cvt_pk_bf16_f32 v138, v138, s0
	v_cvt_pk_bf16_f32 v139, v139, s0
	v_cvt_pk_bf16_f32 v140, v140, s0
	v_cvt_pk_bf16_f32 v141, v141, s0
	v_cvt_pk_bf16_f32 v142, v142, s0
	v_cvt_pk_bf16_f32 v143, v143, s0
	ds_write_b16 v96, v136 offset:4752
	ds_write_b16 v96, v137 offset:4896
	ds_write_b16 v96, v138 offset:5040
	ds_write_b16 v96, v139 offset:5760
	ds_write_b16 v96, v140 offset:5904
	ds_write_b16 v96, v141 offset:6048
	ds_write_b16 v96, v142 offset:6192
	ds_write_b16 v96, v143 offset:6912
	v_mul_f32_e32 v136, 0xbfb8aa3b, v25
	v_mul_f32_e32 v137, 0xbfb8aa3b, v26
	v_mul_f32_e32 v138, 0xbfb8aa3b, v27
	v_mul_f32_e32 v139, 0xbfb8aa3b, v28
	v_mul_f32_e32 v140, 0xbfb8aa3b, v29
	v_mul_f32_e32 v141, 0xbfb8aa3b, v30
	v_mul_f32_e32 v142, 0xbfb8aa3b, v31
	v_exp_f32_e32 v136, v136
	v_exp_f32_e32 v137, v137
	v_exp_f32_e32 v138, v138
	v_exp_f32_e32 v139, v139
	v_exp_f32_e32 v140, v140
	v_exp_f32_e32 v141, v141
	v_exp_f32_e32 v142, v142
	v_add_f32_e32 v136, 1.0, v136
	v_add_f32_e32 v137, 1.0, v137
	v_add_f32_e32 v138, 1.0, v138
	v_add_f32_e32 v139, 1.0, v139
	v_add_f32_e32 v140, 1.0, v140
	v_add_f32_e32 v141, 1.0, v141
	v_add_f32_e32 v142, 1.0, v142
	v_rcp_f32_e32 v136, v136
	v_rcp_f32_e32 v137, v137
	v_rcp_f32_e32 v138, v138
	v_rcp_f32_e32 v139, v139
	v_rcp_f32_e32 v140, v140
	v_rcp_f32_e32 v141, v141
	v_rcp_f32_e32 v142, v142
	v_mul_f32_e32 v136, v25, v136
	v_mul_f32_e32 v137, v26, v137
	v_mul_f32_e32 v138, v27, v138
	v_mul_f32_e32 v139, v28, v139
	v_mul_f32_e32 v140, v29, v140
	v_mul_f32_e32 v141, v30, v141
	v_mul_f32_e32 v142, v31, v142
	v_mul_f32_e32 v136, v9, v136
	v_mul_f32_e32 v137, v10, v137
	v_mul_f32_e32 v138, v11, v138
	v_mul_f32_e32 v139, v12, v139
	v_mul_f32_e32 v140, v13, v140
	v_mul_f32_e32 v141, v14, v141
	v_mul_f32_e32 v142, v15, v142
	v_cvt_pk_bf16_f32 v136, v136, s0
	v_cvt_pk_bf16_f32 v137, v137, s0
	v_cvt_pk_bf16_f32 v138, v138, s0
	v_cvt_pk_bf16_f32 v139, v139, s0
	v_cvt_pk_bf16_f32 v140, v140, s0
	v_cvt_pk_bf16_f32 v141, v141, s0
	v_cvt_pk_bf16_f32 v142, v142, s0
	ds_write_b16 v96, v136 offset:7056
	ds_write_b16 v96, v137 offset:7200
	ds_write_b16 v96, v138 offset:7344
	ds_write_b16 v96, v139 offset:8064
	ds_write_b16 v96, v140 offset:8208
	ds_write_b16 v96, v141 offset:8352
	ds_write_b16 v96, v142 offset:8496
	v_or_b32_e32 v4, 2, v68
	s_waitcnt lgkmcnt(0)
	v_ashrrev_i32_e32 v5, 31, v4
	ds_read_b128 v[0:3], v128
	v_mad_i64_i32 v[6:7], s[0:1], v71, s23, v[4:5]
	v_lshlrev_b64 v[6:7], 10, v[6:7]
	v_lshl_add_u64 v[6:7], s[66:67], 0, v[6:7]
	v_lshl_add_u64 v[6:7], v[6:7], 0, v[176:177]
	v_lshl_add_u64 v[8:9], v[6:7], 0, v[66:67]
	s_waitcnt lgkmcnt(0)
	global_store_dwordx4 v[8:9], v[0:3], off
	ds_read_b128 v[0:3], v128 offset:2304
	v_lshl_add_u64 v[6:7], v[6:7], 0, v[64:65]
	v_mad_i64_i32 v[4:5], s[0:1], v70, s23, v[4:5]
	v_lshlrev_b64 v[4:5], 10, v[4:5]
	s_waitcnt lgkmcnt(0)
	global_store_dwordx4 v[6:7], v[0:3], off
	ds_read_b128 v[0:3], v128 offset:4608
	v_lshl_add_u64 v[4:5], s[66:67], 0, v[4:5]
	v_lshl_add_u64 v[4:5], v[4:5], 0, v[176:177]
	v_lshl_add_u64 v[6:7], v[4:5], 0, v[66:67]
	v_lshl_add_u64 v[4:5], v[4:5], 0, v[64:65]
	s_waitcnt lgkmcnt(0)
	global_store_dwordx4 v[6:7], v[0:3], off
	ds_read_b128 v[0:3], v128 offset:6912
	v_readlane_b32 s0, v254, 11
	s_add_i32 s2, s2, s0
	s_cmp_lt_i32 s2, s3
	s_waitcnt lgkmcnt(0)
	global_store_dwordx4 v[4:5], v[0:3], off
	s_waitcnt lgkmcnt(0)
	s_barrier
	s_cbranch_scc1 .LBB0_1031
